# MoBA pair dealing: each wave starts at its first pair of the block and strides by 8 (no per-pair skip test/branch)
# baseline (speedup 1.0000x reference)
.LBB0_1911:
	s_lshl_b32 s18, s74, 5
	s_add_i32 s18, s18, 0
	s_add_i32 s18, s18, 0x23000
	v_mov_b32_e32 v1, s18
	ds_read_b32 v2, v1
	s_waitcnt lgkmcnt(1)
	ds_read_b32 v3, v1 offset:4
	ds_read_b32 v4, v1 offset:8
	ds_read_b32 v5, v1 offset:12
	ds_read_b32 v6, v1 offset:16
	s_waitcnt lgkmcnt(3)
	v_add_u32_e32 v2, v3, v2
	s_waitcnt lgkmcnt(2)
	v_add_u32_e32 v2, v2, v4
	ds_read_b32 v3, v1 offset:20
	ds_read_b32 v4, v1 offset:24
	ds_read_b32 v1, v1 offset:28
	s_waitcnt lgkmcnt(4)
	v_add_u32_e32 v2, v2, v5
	s_waitcnt lgkmcnt(3)
	v_add_u32_e32 v2, v2, v6
	s_waitcnt lgkmcnt(2)
	v_add_u32_e32 v2, v2, v3
	s_waitcnt lgkmcnt(1)
	v_add_u32_e32 v2, v2, v4
	s_waitcnt lgkmcnt(0)
	v_add_u32_e32 v1, v2, v1
	s_nop 0
	v_readfirstlane_b32 s75, v1
	s_add_i32 s18, s75, 31
	s_ashr_i32 s77, s18, 5
	s_add_i32 s18, s77, 1
	s_ashr_i32 s76, s18, 1
	s_cmp_lt_i32 s76, 1
	s_cbranch_scc1 .LBB0_1910
	v_lshl_or_b32 v166, s74, 8, v225
	v_lshl_add_u64 v[2:3], s[72:73], 0, v[166:167]
	v_lshlrev_b64 v[2:3], 11, v[2:3]
	v_lshlrev_b32_e32 v1, 1, v184
	v_or_b32_e32 v2, v2, v1
	v_lshl_add_u64 v[190:191], s[40:41], 0, v[2:3]
	v_lshl_add_u64 v[192:193], s[42:43], 0, v[2:3]
	v_or_b32_e32 v2, 8, v166
	v_mov_b32_e32 v3, v167
	v_lshl_add_u64 v[2:3], s[72:73], 0, v[2:3]
	v_lshlrev_b64 v[2:3], 11, v[2:3]
	v_or_b32_e32 v2, v2, v1
	v_lshl_add_u64 v[194:195], s[40:41], 0, v[2:3]
	v_lshl_add_u64 v[198:199], s[42:43], 0, v[2:3]
	v_or_b32_e32 v2, 16, v166
	v_mov_b32_e32 v3, v167
	v_lshl_add_u64 v[2:3], s[72:73], 0, v[2:3]
	v_lshlrev_b64 v[2:3], 11, v[2:3]
	v_or_b32_e32 v2, v2, v1
	v_lshl_add_u64 v[200:201], s[40:41], 0, v[2:3]
	v_lshl_add_u64 v[202:203], s[42:43], 0, v[2:3]
	v_or_b32_e32 v2, 24, v166
	v_mov_b32_e32 v3, v167
	v_lshl_add_u64 v[2:3], s[72:73], 0, v[2:3]
	v_lshlrev_b64 v[2:3], 11, v[2:3]
	v_or_b32_e32 v2, v2, v1
	v_lshl_add_u64 v[204:205], s[40:41], 0, v[2:3]
	v_lshl_add_u64 v[206:207], s[42:43], 0, v[2:3]
	v_or_b32_e32 v2, 32, v166
	v_mov_b32_e32 v3, v167
	v_lshl_add_u64 v[2:3], s[72:73], 0, v[2:3]
	v_lshlrev_b64 v[2:3], 11, v[2:3]
	v_or_b32_e32 v2, v2, v1
	v_lshl_add_u64 v[208:209], s[40:41], 0, v[2:3]
	v_lshl_add_u64 v[210:211], s[42:43], 0, v[2:3]
	v_or_b32_e32 v2, 40, v166
	v_mov_b32_e32 v3, v167
	v_lshl_add_u64 v[2:3], s[72:73], 0, v[2:3]
	v_lshlrev_b64 v[2:3], 11, v[2:3]
	v_or_b32_e32 v2, v2, v1
	v_lshl_add_u64 v[212:213], s[40:41], 0, v[2:3]
	v_lshl_add_u64 v[214:215], s[42:43], 0, v[2:3]
	v_or_b32_e32 v2, 48, v166
	v_mov_b32_e32 v3, v167
	v_lshl_add_u64 v[2:3], s[72:73], 0, v[2:3]
	v_lshlrev_b64 v[2:3], 11, v[2:3]
	v_or_b32_e32 v2, v2, v1
	v_or_b32_e32 v166, 56, v166
	v_lshl_add_u64 v[216:217], s[40:41], 0, v[2:3]
	v_lshl_add_u64 v[218:219], s[42:43], 0, v[2:3]
	v_lshl_add_u64 v[2:3], s[72:73], 0, v[166:167]
	s_lshl_b32 s18, s29, 2
	v_lshlrev_b64 v[2:3], 11, v[2:3]
	s_add_i32 s78, s18, 0
	v_or_b32_e32 v2, v2, v1
	s_add_i32 s77, s77, -1
	s_add_i32 s78, s78, 0x23200
	v_lshl_add_u64 v[220:221], s[40:41], 0, v[2:3]
	v_lshl_add_u64 v[222:223], s[42:43], 0, v[2:3]
	s_sub_i32 s79, s82, s28
	s_and_b32 s79, s79, 7
	s_cmp_ge_u32 s79, s76
	s_cbranch_scc1 .LBB0_1910
	s_branch .LBB0_1915

.LBB0_1914:
	s_add_i32 s79, s79, 8
	s_cmp_ge_u32 s79, s76
	s_cbranch_scc1 .LBB0_1910
.LBB0_1915:
	s_lshl_b32 s22, s79, 1
	s_cmp_lt_i32 s22, s77
	s_cselect_b64 s[20:21], -1, 0
	s_lshl_b32 s18, s79, 6
	s_or_b32 s23, s18, 32
	v_or_b32_e32 v1, s18, v197
	v_or_b32_e32 v2, s23, v197
	s_waitcnt lgkmcnt(0)
	v_mov_b32_e32 v3, s18
	v_cmp_gt_i32_e64 s[18:19], s75, v1
	v_mov_b32_e32 v4, s23
	v_cmp_gt_i32_e64 s[24:25], s75, v2
	v_cndmask_b32_e64 v1, v3, v1, s[18:19]
	v_lshl_add_u32 v166, v1, 2, s78
	v_cndmask_b32_e64 v2, v4, v2, s[24:25]
	v_cndmask_b32_e64 v2, v3, v2, s[20:21]
	ds_read_b32 v1, v166
	v_lshl_add_u32 v181, v2, 2, s78
	ds_read_b32 v6, v181
	v_mov_b32_e32 v3, s71
	v_add_u32_e32 v242, v231, v164
	s_waitcnt lgkmcnt(1)
	v_or_b32_sdwa v2, s70, v1 dst_sel:DWORD dst_unused:UNUSED_PAD src0_sel:DWORD src1_sel:BYTE_0
	v_lshlrev_b64 v[4:5], 11, v[2:3]
	s_waitcnt lgkmcnt(0)
	v_or_b32_sdwa v2, s70, v6 dst_sel:DWORD dst_unused:UNUSED_PAD src0_sel:DWORD src1_sel:BYTE_0
	v_lshlrev_b64 v[2:3], 11, v[2:3]
	v_lshl_add_u64 v[14:15], v[186:187], 0, v[4:5]
	v_lshl_add_u64 v[48:49], v[186:187], 0, v[2:3]
	global_load_dwordx4 v[2:5], v[14:15], off
	global_load_dwordx4 v[6:9], v[14:15], off offset:32
	global_load_dwordx4 v[10:13], v[14:15], off offset:64
	global_load_dwordx4 v[32:35], v[14:15], off offset:96
	global_load_dwordx4 v[36:39], v[48:49], off
	global_load_dwordx4 v[40:43], v[48:49], off offset:32
	global_load_dwordx4 v[44:47], v[48:49], off offset:64
	s_nop 0
	global_load_dwordx4 v[48:51], v[48:49], off offset:96
	s_nop 0
	global_load_dwordx4 v[52:55], v[190:191], off
	global_load_dwordx4 v[56:59], v[192:193], off
	global_load_dwordx4 v[60:63], v[194:195], off
	global_load_dwordx4 v[64:67], v[198:199], off
	global_load_dwordx4 v[68:71], v[200:201], off
	global_load_dwordx4 v[72:75], v[202:203], off
	global_load_dwordx4 v[76:79], v[204:205], off
	global_load_dwordx4 v[92:95], v[206:207], off
	global_load_dwordx4 v[128:131], v[208:209], off
	global_load_dwordx4 v[132:135], v[210:211], off
	global_load_dwordx4 v[136:139], v[212:213], off
	global_load_dwordx4 v[140:143], v[214:215], off
	global_load_dwordx4 v[144:147], v[216:217], off
	global_load_dwordx4 v[148:151], v[218:219], off
	global_load_dwordx4 v[152:155], v[220:221], off
	global_load_dwordx4 v[156:159], v[222:223], off
	v_add_u32_e32 v243, v232, v226
	v_add_u32_e32 v244, v233, v227
	v_bfrev_b32_e32 v80, 1
	v_mov_b32_e32 v81, v80
	v_mov_b32_e32 v82, v80
	v_mov_b32_e32 v83, v80
	v_mov_b32_e32 v84, v80
	v_mov_b32_e32 v85, v80
	v_mov_b32_e32 v86, v80
	v_mov_b32_e32 v87, v80
	v_mov_b32_e32 v88, v80
	v_mov_b32_e32 v89, v80
	v_mov_b32_e32 v90, v80
	v_mov_b32_e32 v91, v80
	s_cmp_ge_i32 s22, s77
	s_waitcnt vmcnt(23)
	ds_write_b128 v242, v[2:5] offset:8704
	s_waitcnt vmcnt(22)
	ds_write_b128 v242, v[6:9] offset:8736
	s_waitcnt vmcnt(21)
	ds_write_b128 v242, v[10:13] offset:8768
	s_waitcnt vmcnt(20)
	ds_write_b128 v242, v[32:35] offset:8800
	s_waitcnt vmcnt(19)
	ds_write_b128 v242, v[36:39] offset:13312
	s_waitcnt vmcnt(18)
	ds_write_b128 v242, v[40:43] offset:13344
	s_waitcnt vmcnt(17)
	ds_write_b128 v242, v[44:47] offset:13376
	s_waitcnt vmcnt(16)
	ds_write_b128 v242, v[48:51] offset:13408
	s_waitcnt vmcnt(15)
	ds_write_b128 v243, v[52:55]
	s_waitcnt vmcnt(14)
	ds_write_b128 v244, v[56:59] offset:4608
	s_waitcnt vmcnt(13)
	ds_write_b128 v243, v[60:63] offset:1152
	s_waitcnt vmcnt(12)
	ds_write_b128 v244, v[64:67] offset:5120
	s_waitcnt vmcnt(11)
	ds_write_b128 v243, v[68:71] offset:2304
	s_waitcnt vmcnt(10)
	ds_write_b128 v244, v[72:75] offset:5632
	s_waitcnt vmcnt(9)
	ds_write_b128 v243, v[76:79] offset:3456
	s_waitcnt vmcnt(8)
	ds_write_b128 v244, v[92:95] offset:6144
	s_waitcnt lgkmcnt(0)
	ds_read_b128 v[48:51], v242
	ds_read_b128 v[2:5], v242 offset:8704
	v_mov_b32_e32 v92, v80
	v_mov_b32_e32 v93, v80
	v_mov_b32_e32 v94, v80
	v_mov_b32_e32 v95, v80
	v_mov_b64_e32 v[32:33], v[80:81]
	v_mov_b64_e32 v[34:35], v[82:83]
	v_mov_b64_e32 v[36:37], v[84:85]
	v_mov_b64_e32 v[38:39], v[86:87]
	v_mov_b64_e32 v[40:41], v[88:89]
	v_mov_b64_e32 v[42:43], v[90:91]
	v_mov_b64_e32 v[44:45], v[92:93]
	v_mov_b64_e32 v[46:47], v[94:95]
	ds_read_b128 v[52:55], v242 offset:32
	ds_read_b128 v[6:9], v242 offset:8736
	s_waitcnt lgkmcnt(2)
	v_mfma_f32_32x32x16_bf16 v[32:47], v[48:51], v[2:5], v[32:47]
	s_waitcnt lgkmcnt(0)
	v_mfma_f32_32x32x16_bf16 v[32:47], v[52:55], v[6:9], v[32:47]
	ds_read_b128 v[56:59], v242 offset:64
	ds_read_b128 v[2:5], v242 offset:8768
	ds_read_b128 v[60:63], v242 offset:96
	ds_read_b128 v[6:9], v242 offset:8800
	s_waitcnt lgkmcnt(2)
	v_mfma_f32_32x32x16_bf16 v[32:47], v[56:59], v[2:5], v[32:47]
	s_waitcnt lgkmcnt(0)
	v_mfma_f32_32x32x16_bf16 v[32:47], v[60:63], v[6:9], v[32:47]
	s_cbranch_scc1 .LBB0_1918
	ds_read_b128 v[64:67], v242 offset:13312
	ds_read_b128 v[68:71], v242 offset:13344
	v_mov_b32_e32 v14, v0
	v_mov_b32_e32 v15, v0
	v_mov_b32_e32 v1, v0
	v_mov_b32_e32 v2, v0
	v_mov_b32_e32 v3, v0
	v_mov_b32_e32 v4, v0
	v_mov_b32_e32 v5, v0
	v_mov_b32_e32 v6, v0
	v_mov_b32_e32 v7, v0
	v_mov_b32_e32 v8, v0
	v_mov_b32_e32 v9, v0
	v_mov_b32_e32 v10, v0
	v_mov_b32_e32 v11, v0
	v_mov_b32_e32 v12, v0
	v_mov_b32_e32 v13, v0
	v_mov_b64_e32 v[94:95], v[14:15]
	v_mov_b64_e32 v[92:93], v[12:13]
	v_mov_b64_e32 v[90:91], v[10:11]
	v_mov_b64_e32 v[88:89], v[8:9]
	v_mov_b64_e32 v[86:87], v[6:7]
	v_mov_b64_e32 v[84:85], v[4:5]
	v_mov_b64_e32 v[82:83], v[2:3]
	v_mov_b64_e32 v[80:81], v[0:1]
	ds_read_b128 v[2:5], v242 offset:13376
	ds_read_b128 v[6:9], v242 offset:13408
	s_waitcnt lgkmcnt(3)
	v_mfma_f32_32x32x16_bf16 v[80:95], v[48:51], v[64:67], v[80:95]
	s_waitcnt lgkmcnt(2)
	v_mfma_f32_32x32x16_bf16 v[80:95], v[52:55], v[68:71], v[80:95]
	s_waitcnt lgkmcnt(1)
	v_mfma_f32_32x32x16_bf16 v[80:95], v[56:59], v[2:5], v[80:95]
	s_waitcnt lgkmcnt(0)
	v_mfma_f32_32x32x16_bf16 v[80:95], v[60:63], v[6:9], v[80:95]
